# SwiGLU epilogue: per-row RMSNorm scales computed one unit ahead (next unit ssq loads overlapped with the row math, scales passed through a private LDS slot) so the epilogue no longer drains vmcnt at i
# speedup vs baseline: 1.0008x; 1.0008x over previous
.LBB0_270:
	v_readlane_b32 s16, v255, 40
	s_waitcnt lgkmcnt(0)
	s_add_u32 s10, s10, 0x9200000
	v_readlane_b32 s17, v255, 41
	s_addc_u32 s11, s11, 0
	s_lshl_b64 s[16:17], s[16:17], 2
	s_add_u32 s4, s4, s16
	s_addc_u32 s5, s5, s17
	s_lshl_b32 s7, s15, 5
	s_and_b32 s15, s7, 0x60
	s_add_i32 m0, s40, 0x18000
	v_lshl_add_u64 v[6:7], v[6:7], 0, s[60:61]
	s_lshl_b32 s18, s14, 13
	s_lshl_b32 s19, s15, 7
	s_waitcnt vmcnt(2)
	s_barrier
	global_load_lds_dwordx4 v[6:7], off
	v_lshl_add_u64 v[4:5], v[4:5], 0, s[60:61]
	s_add_i32 m0, s40, 0x1a000
	s_add_i32 s44, s40, 0x8000
	s_add_i32 s45, s40, 0xa000
	global_load_lds_dwordx4 v[4:5], off
	v_lshl_add_u64 v[0:1], v[0:1], 0, s[60:61]
	s_mov_b32 m0, s44
	s_add_u32 s16, s30, 0x40080
	global_load_lds_dwordx4 v[0:1], off
	v_lshl_add_u64 v[0:1], v[2:3], 0, s[60:61]
	s_mov_b32 m0, s45
	s_addc_u32 s17, s31, 0
	global_load_lds_dwordx4 v[0:1], off
	s_add_i32 m0, s40, 0x1c000
	v_lshl_add_u64 v[0:1], s[16:17], 0, v[112:113]
	global_load_lds_dwordx4 v[0:1], off
	v_lshl_add_u64 v[0:1], s[16:17], 0, v[154:155]
	s_add_i32 m0, s40, 0x1e000
	v_bfe_u32 v2, v8, 4, 2
	global_load_lds_dwordx4 v[0:1], off
	v_and_b32_e32 v1, 15, v8
	v_lshlrev_b32_e32 v0, 4, v2
	v_lshlrev_b32_e32 v3, 2, v8
	v_lshl_or_b32 v203, s14, 6, v1
	v_lshl_or_b32 v1, v1, 6, v0
	v_and_b32_e32 v3, 32, v3
	v_bitop3_b32 v4, v1, s18, v3 bitop3:0xde
	v_bitop3_b32 v204, v1, s19, v3 bitop3:0xde
	v_mov_b32_e32 v1, v113
	v_lshl_add_u64 v[0:1], s[4:5], 0, v[0:1]
	s_mov_b64 s[4:5], 0x1d200000
	v_lshl_add_u64 v[160:161], v[0:1], 0, s[4:5]
	v_lshlrev_b32_e32 v0, 14, v13
	v_and_b32_e32 v0, 0xffff8000, v0
	v_lshl_add_u32 v0, v12, 11, v0
	v_and_b32_e32 v1, 1, v13
	v_lshl_or_b32 v0, v1, 6, v0
	v_lshl_add_u32 v162, v14, 1, v0
	v_lshlrev_b32_e32 v0, 14, v9
	v_and_b32_e32 v0, 0xffff8000, v0
	s_waitcnt vmcnt(6)
	v_lshl_add_u32 v0, v10, 11, v0
	v_and_b32_e32 v1, 1, v9
	s_cmpk_lt_u32 s13, 0x100
	v_lshl_or_b32 v0, v1, 6, v0
	s_sext_i32_i16 s7, s12
	s_cselect_b64 s[12:13], -1, 0
	v_lshl_or_b32 v205, v2, 3, s15
	v_mov_b32_e32 v163, v113
	v_lshl_add_u32 v164, v11, 1, v0
	v_mov_b32_e32 v165, v113
	s_mov_b32 s47, 0
	v_add_u32_e32 v206, 0, v4
	v_lshl_add_u32 v32, s6, 8, v203
	v_mov_b32_e32 v33, 0
	v_lshlrev_b64 v[32:33], 6, v[32:33]
	v_lshl_add_u64 v[32:33], v[160:161], 0, v[32:33]
	global_load_dwordx4 v[0:3], v[32:33], off
	global_load_dwordx4 v[4:7], v[32:33], off offset:1024
	global_load_dwordx4 v[8:11], v[32:33], off offset:2048
	global_load_dwordx4 v[12:15], v[32:33], off offset:3072
	v_lshl_add_u32 v32, s6, 8, v203
	v_add_u32_e32 v32, 0x80, v32
	v_mov_b32_e32 v33, 0
	v_lshlrev_b64 v[32:33], 6, v[32:33]
	v_lshl_add_u64 v[32:33], v[160:161], 0, v[32:33]
	global_load_dwordx4 v[16:19], v[32:33], off
	global_load_dwordx4 v[20:23], v[32:33], off offset:1024
	global_load_dwordx4 v[24:27], v[32:33], off offset:2048
	global_load_dwordx4 v[28:31], v[32:33], off offset:3072
	v_and_b32_e32 v34, 64, v245
	v_add_u32_e32 v36, 64, v34
	v_xor_b32_e32 v34, 16, v245
	v_cmp_lt_i32_e32 vcc, v34, v36
	s_nop 1
	v_cndmask_b32_e32 v34, v245, v34, vcc
	v_lshlrev_b32_e32 v34, 2, v34
	v_xor_b32_e32 v35, 32, v245
	v_cmp_lt_i32_e32 vcc, v35, v36
	s_nop 1
	v_cndmask_b32_e32 v35, v245, v35, vcc
	v_lshlrev_b32_e32 v35, 2, v35
	s_mov_b32 s100, 0x3a800000
	v_lshrrev_b32_e32 v38, 6, v224
	v_and_b32_e32 v39, 15, v224
	v_lshlrev_b32_e32 v38, 9, v38
	v_lshl_or_b32 v38, v39, 5, v38
	v_add_u32_e32 v38, 0x20000, v38
	s_waitcnt vmcnt(0)
	v_add_f32_e32 v1, v1, v0
	v_add_f32_e32 v3, v2, v3
	v_add_f32_e32 v5, v5, v4
	v_add_f32_e32 v7, v6, v7
	v_add_f32_e32 v9, v9, v8
	v_add_f32_e32 v11, v10, v11
	v_add_f32_e32 v13, v13, v12
	v_add_f32_e32 v15, v14, v15
	v_add_f32_e32 v17, v17, v16
	v_add_f32_e32 v19, v18, v19
	v_add_f32_e32 v21, v21, v20
	v_add_f32_e32 v23, v22, v23
	v_add_f32_e32 v25, v25, v24
	v_add_f32_e32 v27, v26, v27
	v_add_f32_e32 v29, v29, v28
	v_add_f32_e32 v31, v30, v31
	v_add_f32_e32 v0, v1, v3
	v_add_f32_e32 v4, v5, v7
	v_add_f32_e32 v8, v9, v11
	v_add_f32_e32 v12, v13, v15
	v_add_f32_e32 v16, v17, v19
	v_add_f32_e32 v20, v21, v23
	v_add_f32_e32 v24, v25, v27
	v_add_f32_e32 v28, v29, v31
	ds_bpermute_b32 v1, v34, v0
	ds_bpermute_b32 v5, v34, v4
	ds_bpermute_b32 v9, v34, v8
	ds_bpermute_b32 v13, v34, v12
	ds_bpermute_b32 v17, v34, v16
	ds_bpermute_b32 v21, v34, v20
	ds_bpermute_b32 v25, v34, v24
	ds_bpermute_b32 v29, v34, v28
	s_waitcnt lgkmcnt(0)
	v_add_f32_e32 v0, v0, v1
	v_add_f32_e32 v4, v4, v5
	v_add_f32_e32 v8, v8, v9
	v_add_f32_e32 v12, v12, v13
	v_add_f32_e32 v16, v16, v17
	v_add_f32_e32 v20, v20, v21
	v_add_f32_e32 v24, v24, v25
	v_add_f32_e32 v28, v28, v29
	ds_bpermute_b32 v1, v35, v0
	ds_bpermute_b32 v5, v35, v4
	ds_bpermute_b32 v9, v35, v8
	ds_bpermute_b32 v13, v35, v12
	ds_bpermute_b32 v17, v35, v16
	ds_bpermute_b32 v21, v35, v20
	ds_bpermute_b32 v25, v35, v24
	ds_bpermute_b32 v29, v35, v28
	s_waitcnt lgkmcnt(0)
	v_add_f32_e32 v0, v0, v1
	v_add_f32_e32 v4, v4, v5
	v_add_f32_e32 v8, v8, v9
	v_add_f32_e32 v12, v12, v13
	v_add_f32_e32 v16, v16, v17
	v_add_f32_e32 v20, v20, v21
	v_add_f32_e32 v24, v24, v25
	v_add_f32_e32 v28, v28, v29
	v_mov_b32_e32 v37, 0x358637bd
	v_fma_f32 v0, v0, s100, v37
	v_fma_f32 v4, v4, s100, v37
	v_fma_f32 v8, v8, s100, v37
	v_fma_f32 v12, v12, s100, v37
	v_fma_f32 v16, v16, s100, v37
	v_fma_f32 v20, v20, s100, v37
	v_fma_f32 v24, v24, s100, v37
	v_fma_f32 v28, v28, s100, v37
	v_rsq_f32_e32 v0, v0
	v_rsq_f32_e32 v4, v4
	v_rsq_f32_e32 v8, v8
	v_rsq_f32_e32 v12, v12
	v_rsq_f32_e32 v16, v16
	v_rsq_f32_e32 v20, v20
	v_rsq_f32_e32 v24, v24
	v_rsq_f32_e32 v28, v28
	s_nop 0
	ds_write_b32 v38, v0
	ds_write_b32 v38, v4 offset:4
	ds_write_b32 v38, v8 offset:8
	ds_write_b32 v38, v12 offset:12
	ds_write_b32 v38, v16 offset:16
	ds_write_b32 v38, v20 offset:20
	ds_write_b32 v38, v24 offset:24
	ds_write_b32 v38, v28 offset:28
	s_waitcnt lgkmcnt(0)
	s_barrier
	s_branch .LBB0_273

.LBB0_279:
	v_lshl_add_u32 v176, s6, 8, v203
	v_or_b32_e32 v184, 16, v176
	v_or_b32_e32 v182, 32, v176
	v_or_b32_e32 v180, 48, v176
	v_add_u32_e32 v178, 0x80, v176
	v_add_u32_e32 v174, 0x90, v176
	v_add_u32_e32 v172, 0xa0, v176
	v_lshl_or_b32 v194, s7, 7, v205
	v_add_u32_e32 v166, 0xb0, v176
	v_ashrrev_i32_e32 v195, 31, v194
	v_and_b32_e32 v173, 64, v245
	v_xor_b32_e32 v167, 16, v245
	v_add_u32_e32 v175, 64, v173
	v_cmp_lt_i32_e32 vcc, v167, v175
	s_mov_b32 s22, 0x3a800000
	s_nop 1
	v_cndmask_b32_e32 v167, v245, v167, vcc
	v_lshlrev_b32_e32 v173, 2, v167
	v_xor_b32_e32 v167, 32, v245
	v_cmp_lt_i32_e32 vcc, v167, v175
	v_readlane_b32 s50, v255, 34
	s_nop 1
	v_cndmask_b32_e32 v167, v245, v167, vcc
	v_lshlrev_b32_e32 v167, 2, v167
	v_readlane_b32 s62, v255, 36
	v_readlane_b32 s51, v255, 35
	v_readlane_b32 s63, v255, 37
	v_lshrrev_b32_e32 v79, 6, v224
	v_and_b32_e32 v78, 15, v224
	v_lshlrev_b32_e32 v79, 9, v79
	v_lshl_or_b32 v79, v78, 5, v79
	v_add_u32_e32 v79, 0x20000, v79
	ds_read_b32 v168, v79
	ds_read_b32 v208, v79 offset:4
	ds_read_b32 v150, v79 offset:8
	ds_read_b32 v146, v79 offset:12
	ds_read_b32 v122, v79 offset:16
	ds_read_b32 v118, v79 offset:20
	ds_read_b32 v80, v79 offset:24
	ds_read_b32 v76, v79 offset:28
	v_lshlrev_b64 v[170:171], 1, v[194:195]
	v_lshl_add_u64 v[170:171], s[10:11], 0, v[170:171]
	s_waitcnt lgkmcnt(0)
	v_pk_mul_f32 v[142:143], v[142:143], v[168:169] op_sel_hi:[1,0]
	v_pk_mul_f32 v[144:145], v[144:145], v[168:169] op_sel_hi:[1,0]
	v_pk_mul_f32 v[134:135], v[134:135], v[168:169] op_sel_hi:[1,0]
	v_pk_mul_f32 v[136:137], v[136:137], v[168:169] op_sel_hi:[1,0]
	v_mul_f32_e32 v152, 0xbfb8aa3b, v142
	v_mul_f32_e32 v153, 0xbfb8aa3b, v143
	v_mul_f32_e32 v148, 0xbfb8aa3b, v144
	v_mul_f32_e32 v149, 0xbfb8aa3b, v145
	v_mul_f32_e32 v124, 0xbfb8aa3b, v134
	v_mul_f32_e32 v125, 0xbfb8aa3b, v135
	v_mul_f32_e32 v120, 0xbfb8aa3b, v136
	v_mul_f32_e32 v121, 0xbfb8aa3b, v137
	v_pk_mul_f32 v[138:139], v[138:139], v[168:169] op_sel_hi:[1,0]
	v_pk_mul_f32 v[140:141], v[140:141], v[168:169] op_sel_hi:[1,0]
	v_pk_mul_f32 v[130:131], v[130:131], v[168:169] op_sel_hi:[1,0]
	v_pk_mul_f32 v[132:133], v[132:133], v[168:169] op_sel_hi:[1,0]
	v_exp_f32_e32 v152, v152
	v_exp_f32_e32 v153, v153
	v_exp_f32_e32 v148, v148
	v_exp_f32_e32 v149, v149
	v_exp_f32_e32 v124, v124
	v_exp_f32_e32 v125, v125
	v_exp_f32_e32 v120, v120
	v_exp_f32_e32 v121, v121
	v_mad_i64_i32 v[82:83], vcc, v176, s52, v[170:171]
	v_add_f32_e32 v152, 1.0, v152
	v_add_f32_e32 v153, 1.0, v153
	v_add_f32_e32 v148, 1.0, v148
	v_add_f32_e32 v149, 1.0, v149
	v_add_f32_e32 v124, 1.0, v124
	v_add_f32_e32 v125, 1.0, v125
	v_add_f32_e32 v120, 1.0, v120
	v_add_f32_e32 v121, 1.0, v121
	v_rcp_f32_e32 v152, v152
	v_rcp_f32_e32 v153, v153
	v_rcp_f32_e32 v148, v148
	v_rcp_f32_e32 v149, v149
	v_rcp_f32_e32 v124, v124
	v_rcp_f32_e32 v125, v125
	v_rcp_f32_e32 v120, v120
	v_rcp_f32_e32 v121, v121
	s_nop 0
	v_pk_mul_f32 v[142:143], v[142:143], v[152:153]
	v_pk_mul_f32 v[144:145], v[144:145], v[148:149]
	v_pk_mul_f32 v[134:135], v[134:135], v[124:125]
	v_pk_mul_f32 v[136:137], v[136:137], v[120:121]
	v_pk_mul_f32 v[138:139], v[138:139], v[142:143]
	v_pk_mul_f32 v[140:141], v[140:141], v[144:145]
	v_pk_mul_f32 v[130:131], v[130:131], v[134:135]
	v_pk_mul_f32 v[132:133], v[132:133], v[136:137]
	v_cvt_pk_bf16_f32 v138, v138, v139
	v_cvt_pk_bf16_f32 v139, v140, v141
	v_cvt_pk_bf16_f32 v140, v130, v131
	v_cvt_pk_bf16_f32 v141, v132, v133
	global_store_dwordx4 v[82:83], v[138:141], off nt
	v_pk_mul_f32 v[126:127], v[126:127], v[208:209] op_sel_hi:[1,0]
	v_pk_mul_f32 v[128:129], v[128:129], v[208:209] op_sel_hi:[1,0]
	v_pk_mul_f32 v[108:109], v[108:109], v[208:209] op_sel_hi:[1,0]
	v_pk_mul_f32 v[110:111], v[110:111], v[208:209] op_sel_hi:[1,0]
	v_mul_f32_e32 v152, 0xbfb8aa3b, v126
	v_mul_f32_e32 v153, 0xbfb8aa3b, v127
	v_mul_f32_e32 v148, 0xbfb8aa3b, v128
	v_mul_f32_e32 v149, 0xbfb8aa3b, v129
	v_mul_f32_e32 v124, 0xbfb8aa3b, v108
	v_mul_f32_e32 v125, 0xbfb8aa3b, v109
	v_mul_f32_e32 v120, 0xbfb8aa3b, v110
	v_mul_f32_e32 v121, 0xbfb8aa3b, v111
	v_pk_mul_f32 v[114:115], v[114:115], v[208:209] op_sel_hi:[1,0]
	v_pk_mul_f32 v[116:117], v[116:117], v[208:209] op_sel_hi:[1,0]
	v_pk_mul_f32 v[104:105], v[104:105], v[208:209] op_sel_hi:[1,0]
	v_pk_mul_f32 v[106:107], v[106:107], v[208:209] op_sel_hi:[1,0]
	v_exp_f32_e32 v152, v152
	v_exp_f32_e32 v153, v153
	v_exp_f32_e32 v148, v148
	v_exp_f32_e32 v149, v149
	v_exp_f32_e32 v124, v124
	v_exp_f32_e32 v125, v125
	v_exp_f32_e32 v120, v120
	v_exp_f32_e32 v121, v121
	v_mad_i64_i32 v[82:83], vcc, v184, s52, v[170:171]
	v_add_f32_e32 v152, 1.0, v152
	v_add_f32_e32 v153, 1.0, v153
	v_add_f32_e32 v148, 1.0, v148
	v_add_f32_e32 v149, 1.0, v149
	v_add_f32_e32 v124, 1.0, v124
	v_add_f32_e32 v125, 1.0, v125
	v_add_f32_e32 v120, 1.0, v120
	v_add_f32_e32 v121, 1.0, v121
	v_rcp_f32_e32 v152, v152
	v_rcp_f32_e32 v153, v153
	v_rcp_f32_e32 v148, v148
	v_rcp_f32_e32 v149, v149
	v_rcp_f32_e32 v124, v124
	v_rcp_f32_e32 v125, v125
	v_rcp_f32_e32 v120, v120
	v_rcp_f32_e32 v121, v121
	s_nop 0
	v_pk_mul_f32 v[126:127], v[126:127], v[152:153]
	v_pk_mul_f32 v[128:129], v[128:129], v[148:149]
	v_pk_mul_f32 v[108:109], v[108:109], v[124:125]
	v_pk_mul_f32 v[110:111], v[110:111], v[120:121]
	v_pk_mul_f32 v[114:115], v[114:115], v[126:127]
	v_pk_mul_f32 v[116:117], v[116:117], v[128:129]
	v_pk_mul_f32 v[104:105], v[104:105], v[108:109]
	v_pk_mul_f32 v[106:107], v[106:107], v[110:111]
	v_cvt_pk_bf16_f32 v114, v114, v115
	v_cvt_pk_bf16_f32 v115, v116, v117
	v_cvt_pk_bf16_f32 v116, v104, v105
	v_cvt_pk_bf16_f32 v117, v106, v107
	global_store_dwordx4 v[82:83], v[114:117], off nt
	v_lshl_add_u32 v210, s16, 8, v203
	v_mov_b32_e32 v211, 0
	v_lshlrev_b64 v[210:211], 6, v[210:211]
	v_lshl_add_u64 v[210:211], v[160:161], 0, v[210:211]
	global_load_dwordx4 v[142:145], v[210:211], off
	global_load_dwordx4 v[134:137], v[210:211], off offset:1024
	global_load_dwordx4 v[130:133], v[210:211], off offset:2048
	global_load_dwordx4 v[138:141], v[210:211], off offset:3072
	v_lshl_add_u32 v210, s16, 8, v203
	v_add_u32_e32 v210, 0x80, v210
	v_mov_b32_e32 v211, 0
	v_lshlrev_b64 v[210:211], 6, v[210:211]
	v_lshl_add_u64 v[210:211], v[160:161], 0, v[210:211]
	global_load_dwordx4 v[126:129], v[210:211], off
	global_load_dwordx4 v[108:111], v[210:211], off offset:1024
	global_load_dwordx4 v[104:107], v[210:211], off offset:2048
	global_load_dwordx4 v[114:117], v[210:211], off offset:3072
	v_pk_mul_f32 v[100:101], v[100:101], v[150:151] op_sel_hi:[1,0]
	v_pk_mul_f32 v[102:103], v[102:103], v[150:151] op_sel_hi:[1,0]
	v_pk_mul_f32 v[92:93], v[92:93], v[150:151] op_sel_hi:[1,0]
	v_pk_mul_f32 v[94:95], v[94:95], v[150:151] op_sel_hi:[1,0]
	v_mul_f32_e32 v152, 0xbfb8aa3b, v100
	v_mul_f32_e32 v153, 0xbfb8aa3b, v101
	v_mul_f32_e32 v148, 0xbfb8aa3b, v102
	v_mul_f32_e32 v149, 0xbfb8aa3b, v103
	v_mul_f32_e32 v124, 0xbfb8aa3b, v92
	v_mul_f32_e32 v125, 0xbfb8aa3b, v93
	v_mul_f32_e32 v120, 0xbfb8aa3b, v94
	v_mul_f32_e32 v121, 0xbfb8aa3b, v95
	v_pk_mul_f32 v[96:97], v[96:97], v[150:151] op_sel_hi:[1,0]
	v_pk_mul_f32 v[98:99], v[98:99], v[150:151] op_sel_hi:[1,0]
	v_pk_mul_f32 v[88:89], v[88:89], v[150:151] op_sel_hi:[1,0]
	v_pk_mul_f32 v[90:91], v[90:91], v[150:151] op_sel_hi:[1,0]
	v_exp_f32_e32 v152, v152
	v_exp_f32_e32 v153, v153
	v_exp_f32_e32 v148, v148
	v_exp_f32_e32 v149, v149
	v_exp_f32_e32 v124, v124
	v_exp_f32_e32 v125, v125
	v_exp_f32_e32 v120, v120
	v_exp_f32_e32 v121, v121
	v_mad_i64_i32 v[82:83], vcc, v182, s52, v[170:171]
	v_add_f32_e32 v152, 1.0, v152
	v_add_f32_e32 v153, 1.0, v153
	v_add_f32_e32 v148, 1.0, v148
	v_add_f32_e32 v149, 1.0, v149
	v_add_f32_e32 v124, 1.0, v124
	v_add_f32_e32 v125, 1.0, v125
	v_add_f32_e32 v120, 1.0, v120
	v_add_f32_e32 v121, 1.0, v121
	v_rcp_f32_e32 v152, v152
	v_rcp_f32_e32 v153, v153
	v_rcp_f32_e32 v148, v148
	v_rcp_f32_e32 v149, v149
	v_rcp_f32_e32 v124, v124
	v_rcp_f32_e32 v125, v125
	v_rcp_f32_e32 v120, v120
	v_rcp_f32_e32 v121, v121
	s_nop 0
	v_pk_mul_f32 v[100:101], v[100:101], v[152:153]
	v_pk_mul_f32 v[102:103], v[102:103], v[148:149]
	v_pk_mul_f32 v[92:93], v[92:93], v[124:125]
	v_pk_mul_f32 v[94:95], v[94:95], v[120:121]
	v_pk_mul_f32 v[96:97], v[96:97], v[100:101]
	v_pk_mul_f32 v[98:99], v[98:99], v[102:103]
	v_pk_mul_f32 v[88:89], v[88:89], v[92:93]
	v_pk_mul_f32 v[90:91], v[90:91], v[94:95]
	v_cvt_pk_bf16_f32 v96, v96, v97
	v_cvt_pk_bf16_f32 v97, v98, v99
	v_cvt_pk_bf16_f32 v98, v88, v89
	v_cvt_pk_bf16_f32 v99, v90, v91
	global_store_dwordx4 v[82:83], v[96:99], off nt
	v_pk_mul_f32 v[84:85], v[84:85], v[146:147] op_sel_hi:[1,0]
	v_pk_mul_f32 v[86:87], v[86:87], v[146:147] op_sel_hi:[1,0]
	v_pk_mul_f32 v[68:69], v[68:69], v[146:147] op_sel_hi:[1,0]
	v_pk_mul_f32 v[70:71], v[70:71], v[146:147] op_sel_hi:[1,0]
	v_mul_f32_e32 v152, 0xbfb8aa3b, v84
	v_mul_f32_e32 v153, 0xbfb8aa3b, v85
	v_mul_f32_e32 v148, 0xbfb8aa3b, v86
	v_mul_f32_e32 v149, 0xbfb8aa3b, v87
	v_mul_f32_e32 v124, 0xbfb8aa3b, v68
	v_mul_f32_e32 v125, 0xbfb8aa3b, v69
	v_mul_f32_e32 v120, 0xbfb8aa3b, v70
	v_mul_f32_e32 v121, 0xbfb8aa3b, v71
	v_pk_mul_f32 v[72:73], v[72:73], v[146:147] op_sel_hi:[1,0]
	v_pk_mul_f32 v[74:75], v[74:75], v[146:147] op_sel_hi:[1,0]
	v_pk_mul_f32 v[64:65], v[64:65], v[146:147] op_sel_hi:[1,0]
	v_pk_mul_f32 v[66:67], v[66:67], v[146:147] op_sel_hi:[1,0]
	v_exp_f32_e32 v152, v152
	v_exp_f32_e32 v153, v153
	v_exp_f32_e32 v148, v148
	v_exp_f32_e32 v149, v149
	v_exp_f32_e32 v124, v124
	v_exp_f32_e32 v125, v125
	v_exp_f32_e32 v120, v120
	v_exp_f32_e32 v121, v121
	v_mad_i64_i32 v[82:83], vcc, v180, s52, v[170:171]
	v_add_f32_e32 v152, 1.0, v152
	v_add_f32_e32 v153, 1.0, v153
	v_add_f32_e32 v148, 1.0, v148
	v_add_f32_e32 v149, 1.0, v149
	v_add_f32_e32 v124, 1.0, v124
	v_add_f32_e32 v125, 1.0, v125
	v_add_f32_e32 v120, 1.0, v120
	v_add_f32_e32 v121, 1.0, v121
	v_rcp_f32_e32 v152, v152
	v_rcp_f32_e32 v153, v153
	v_rcp_f32_e32 v148, v148
	v_rcp_f32_e32 v149, v149
	v_rcp_f32_e32 v124, v124
	v_rcp_f32_e32 v125, v125
	v_rcp_f32_e32 v120, v120
	v_rcp_f32_e32 v121, v121
	s_nop 0
	v_pk_mul_f32 v[84:85], v[84:85], v[152:153]
	v_pk_mul_f32 v[86:87], v[86:87], v[148:149]
	v_pk_mul_f32 v[68:69], v[68:69], v[124:125]
	v_pk_mul_f32 v[70:71], v[70:71], v[120:121]
	v_pk_mul_f32 v[72:73], v[72:73], v[84:85]
	v_pk_mul_f32 v[74:75], v[74:75], v[86:87]
	v_pk_mul_f32 v[64:65], v[64:65], v[68:69]
	v_pk_mul_f32 v[66:67], v[66:67], v[70:71]
	v_cvt_pk_bf16_f32 v72, v72, v73
	v_cvt_pk_bf16_f32 v73, v74, v75
	v_cvt_pk_bf16_f32 v74, v64, v65
	v_cvt_pk_bf16_f32 v75, v66, v67
	global_store_dwordx4 v[82:83], v[72:75], off nt
	v_pk_mul_f32 v[60:61], v[60:61], v[122:123] op_sel_hi:[1,0]
	v_pk_mul_f32 v[62:63], v[62:63], v[122:123] op_sel_hi:[1,0]
	v_pk_mul_f32 v[52:53], v[52:53], v[122:123] op_sel_hi:[1,0]
	v_pk_mul_f32 v[54:55], v[54:55], v[122:123] op_sel_hi:[1,0]
	v_mul_f32_e32 v152, 0xbfb8aa3b, v60
	v_mul_f32_e32 v153, 0xbfb8aa3b, v61
	v_mul_f32_e32 v148, 0xbfb8aa3b, v62
	v_mul_f32_e32 v149, 0xbfb8aa3b, v63
	v_mul_f32_e32 v124, 0xbfb8aa3b, v52
	v_mul_f32_e32 v125, 0xbfb8aa3b, v53
	v_mul_f32_e32 v120, 0xbfb8aa3b, v54
	v_mul_f32_e32 v121, 0xbfb8aa3b, v55
	v_pk_mul_f32 v[56:57], v[56:57], v[122:123] op_sel_hi:[1,0]
	v_pk_mul_f32 v[58:59], v[58:59], v[122:123] op_sel_hi:[1,0]
	v_pk_mul_f32 v[48:49], v[48:49], v[122:123] op_sel_hi:[1,0]
	v_pk_mul_f32 v[50:51], v[50:51], v[122:123] op_sel_hi:[1,0]
	v_exp_f32_e32 v152, v152
	v_exp_f32_e32 v153, v153
	v_exp_f32_e32 v148, v148
	v_exp_f32_e32 v149, v149
	v_exp_f32_e32 v124, v124
	v_exp_f32_e32 v125, v125
	v_exp_f32_e32 v120, v120
	v_exp_f32_e32 v121, v121
	v_mad_i64_i32 v[82:83], vcc, v178, s52, v[170:171]
	v_add_f32_e32 v152, 1.0, v152
	v_add_f32_e32 v153, 1.0, v153
	v_add_f32_e32 v148, 1.0, v148
	v_add_f32_e32 v149, 1.0, v149
	v_add_f32_e32 v124, 1.0, v124
	v_add_f32_e32 v125, 1.0, v125
	v_add_f32_e32 v120, 1.0, v120
	v_add_f32_e32 v121, 1.0, v121
	v_rcp_f32_e32 v152, v152
	v_rcp_f32_e32 v153, v153
	v_rcp_f32_e32 v148, v148
	v_rcp_f32_e32 v149, v149
	v_rcp_f32_e32 v124, v124
	v_rcp_f32_e32 v125, v125
	v_rcp_f32_e32 v120, v120
	v_rcp_f32_e32 v121, v121
	s_nop 0
	v_pk_mul_f32 v[60:61], v[60:61], v[152:153]
	v_pk_mul_f32 v[62:63], v[62:63], v[148:149]
	v_pk_mul_f32 v[52:53], v[52:53], v[124:125]
	v_pk_mul_f32 v[54:55], v[54:55], v[120:121]
	v_pk_mul_f32 v[56:57], v[56:57], v[60:61]
	v_pk_mul_f32 v[58:59], v[58:59], v[62:63]
	v_pk_mul_f32 v[48:49], v[48:49], v[52:53]
	v_pk_mul_f32 v[50:51], v[50:51], v[54:55]
	v_cvt_pk_bf16_f32 v56, v56, v57
	v_cvt_pk_bf16_f32 v57, v58, v59
	v_cvt_pk_bf16_f32 v58, v48, v49
	v_cvt_pk_bf16_f32 v59, v50, v51
	global_store_dwordx4 v[82:83], v[56:59], off nt
	v_pk_mul_f32 v[44:45], v[44:45], v[118:119] op_sel_hi:[1,0]
	v_pk_mul_f32 v[46:47], v[46:47], v[118:119] op_sel_hi:[1,0]
	v_pk_mul_f32 v[36:37], v[36:37], v[118:119] op_sel_hi:[1,0]
	v_pk_mul_f32 v[38:39], v[38:39], v[118:119] op_sel_hi:[1,0]
	v_mul_f32_e32 v152, 0xbfb8aa3b, v44
	v_mul_f32_e32 v153, 0xbfb8aa3b, v45
	v_mul_f32_e32 v148, 0xbfb8aa3b, v46
	v_mul_f32_e32 v149, 0xbfb8aa3b, v47
	v_mul_f32_e32 v124, 0xbfb8aa3b, v36
	v_mul_f32_e32 v125, 0xbfb8aa3b, v37
	v_mul_f32_e32 v120, 0xbfb8aa3b, v38
	v_mul_f32_e32 v121, 0xbfb8aa3b, v39
	v_pk_mul_f32 v[40:41], v[40:41], v[118:119] op_sel_hi:[1,0]
	v_pk_mul_f32 v[42:43], v[42:43], v[118:119] op_sel_hi:[1,0]
	v_pk_mul_f32 v[32:33], v[32:33], v[118:119] op_sel_hi:[1,0]
	v_pk_mul_f32 v[34:35], v[34:35], v[118:119] op_sel_hi:[1,0]
	v_exp_f32_e32 v152, v152
	v_exp_f32_e32 v153, v153
	v_exp_f32_e32 v148, v148
	v_exp_f32_e32 v149, v149
	v_exp_f32_e32 v124, v124
	v_exp_f32_e32 v125, v125
	v_exp_f32_e32 v120, v120
	v_exp_f32_e32 v121, v121
	v_mad_i64_i32 v[82:83], vcc, v174, s52, v[170:171]
	v_add_f32_e32 v152, 1.0, v152
	v_add_f32_e32 v153, 1.0, v153
	v_add_f32_e32 v148, 1.0, v148
	v_add_f32_e32 v149, 1.0, v149
	v_add_f32_e32 v124, 1.0, v124
	v_add_f32_e32 v125, 1.0, v125
	v_add_f32_e32 v120, 1.0, v120
	v_add_f32_e32 v121, 1.0, v121
	v_rcp_f32_e32 v152, v152
	v_rcp_f32_e32 v153, v153
	v_rcp_f32_e32 v148, v148
	v_rcp_f32_e32 v149, v149
	v_rcp_f32_e32 v124, v124
	v_rcp_f32_e32 v125, v125
	v_rcp_f32_e32 v120, v120
	v_rcp_f32_e32 v121, v121
	s_nop 0
	v_pk_mul_f32 v[44:45], v[44:45], v[152:153]
	v_pk_mul_f32 v[46:47], v[46:47], v[148:149]
	v_pk_mul_f32 v[36:37], v[36:37], v[124:125]
	v_pk_mul_f32 v[38:39], v[38:39], v[120:121]
	v_pk_mul_f32 v[40:41], v[40:41], v[44:45]
	v_pk_mul_f32 v[42:43], v[42:43], v[46:47]
	v_pk_mul_f32 v[32:33], v[32:33], v[36:37]
	v_pk_mul_f32 v[34:35], v[34:35], v[38:39]
	v_cvt_pk_bf16_f32 v40, v40, v41
	v_cvt_pk_bf16_f32 v41, v42, v43
	v_cvt_pk_bf16_f32 v42, v32, v33
	v_cvt_pk_bf16_f32 v43, v34, v35
	global_store_dwordx4 v[82:83], v[40:43], off nt
	v_pk_mul_f32 v[28:29], v[28:29], v[80:81] op_sel_hi:[1,0]
	v_pk_mul_f32 v[30:31], v[30:31], v[80:81] op_sel_hi:[1,0]
	v_pk_mul_f32 v[20:21], v[20:21], v[80:81] op_sel_hi:[1,0]
	v_pk_mul_f32 v[22:23], v[22:23], v[80:81] op_sel_hi:[1,0]
	v_mul_f32_e32 v152, 0xbfb8aa3b, v28
	v_mul_f32_e32 v153, 0xbfb8aa3b, v29
	v_mul_f32_e32 v148, 0xbfb8aa3b, v30
	v_mul_f32_e32 v149, 0xbfb8aa3b, v31
	v_mul_f32_e32 v124, 0xbfb8aa3b, v20
	v_mul_f32_e32 v125, 0xbfb8aa3b, v21
	v_mul_f32_e32 v120, 0xbfb8aa3b, v22
	v_mul_f32_e32 v121, 0xbfb8aa3b, v23
	v_pk_mul_f32 v[24:25], v[24:25], v[80:81] op_sel_hi:[1,0]
	v_pk_mul_f32 v[26:27], v[26:27], v[80:81] op_sel_hi:[1,0]
	v_pk_mul_f32 v[16:17], v[16:17], v[80:81] op_sel_hi:[1,0]
	v_pk_mul_f32 v[18:19], v[18:19], v[80:81] op_sel_hi:[1,0]
	v_exp_f32_e32 v152, v152
	v_exp_f32_e32 v153, v153
	v_exp_f32_e32 v148, v148
	v_exp_f32_e32 v149, v149
	v_exp_f32_e32 v124, v124
	v_exp_f32_e32 v125, v125
	v_exp_f32_e32 v120, v120
	v_exp_f32_e32 v121, v121
	v_mad_i64_i32 v[82:83], vcc, v172, s52, v[170:171]
	v_add_f32_e32 v152, 1.0, v152
	v_add_f32_e32 v153, 1.0, v153
	v_add_f32_e32 v148, 1.0, v148
	v_add_f32_e32 v149, 1.0, v149
	v_add_f32_e32 v124, 1.0, v124
	v_add_f32_e32 v125, 1.0, v125
	v_add_f32_e32 v120, 1.0, v120
	v_add_f32_e32 v121, 1.0, v121
	v_rcp_f32_e32 v152, v152
	v_rcp_f32_e32 v153, v153
	v_rcp_f32_e32 v148, v148
	v_rcp_f32_e32 v149, v149
	v_rcp_f32_e32 v124, v124
	v_rcp_f32_e32 v125, v125
	v_rcp_f32_e32 v120, v120
	v_rcp_f32_e32 v121, v121
	s_nop 0
	v_pk_mul_f32 v[28:29], v[28:29], v[152:153]
	v_pk_mul_f32 v[30:31], v[30:31], v[148:149]
	v_pk_mul_f32 v[20:21], v[20:21], v[124:125]
	v_pk_mul_f32 v[22:23], v[22:23], v[120:121]
	v_pk_mul_f32 v[24:25], v[24:25], v[28:29]
	v_pk_mul_f32 v[26:27], v[26:27], v[30:31]
	v_pk_mul_f32 v[16:17], v[16:17], v[20:21]
	v_pk_mul_f32 v[18:19], v[18:19], v[22:23]
	v_cvt_pk_bf16_f32 v24, v24, v25
	v_cvt_pk_bf16_f32 v25, v26, v27
	v_cvt_pk_bf16_f32 v26, v16, v17
	v_cvt_pk_bf16_f32 v27, v18, v19
	global_store_dwordx4 v[82:83], v[24:27], off nt
	v_pk_mul_f32 v[12:13], v[12:13], v[76:77] op_sel_hi:[1,0]
	v_pk_mul_f32 v[14:15], v[14:15], v[76:77] op_sel_hi:[1,0]
	v_pk_mul_f32 v[4:5], v[4:5], v[76:77] op_sel_hi:[1,0]
	v_pk_mul_f32 v[6:7], v[6:7], v[76:77] op_sel_hi:[1,0]
	v_mul_f32_e32 v152, 0xbfb8aa3b, v12
	v_mul_f32_e32 v153, 0xbfb8aa3b, v13
	v_mul_f32_e32 v148, 0xbfb8aa3b, v14
	v_mul_f32_e32 v149, 0xbfb8aa3b, v15
	v_mul_f32_e32 v124, 0xbfb8aa3b, v4
	v_mul_f32_e32 v125, 0xbfb8aa3b, v5
	v_mul_f32_e32 v120, 0xbfb8aa3b, v6
	v_mul_f32_e32 v121, 0xbfb8aa3b, v7
	v_pk_mul_f32 v[8:9], v[8:9], v[76:77] op_sel_hi:[1,0]
	v_pk_mul_f32 v[10:11], v[10:11], v[76:77] op_sel_hi:[1,0]
	v_pk_mul_f32 v[0:1], v[0:1], v[76:77] op_sel_hi:[1,0]
	v_pk_mul_f32 v[2:3], v[2:3], v[76:77] op_sel_hi:[1,0]
	v_exp_f32_e32 v152, v152
	v_exp_f32_e32 v153, v153
	v_exp_f32_e32 v148, v148
	v_exp_f32_e32 v149, v149
	v_exp_f32_e32 v124, v124
	v_exp_f32_e32 v125, v125
	v_exp_f32_e32 v120, v120
	v_exp_f32_e32 v121, v121
	v_mad_i64_i32 v[82:83], vcc, v166, s52, v[170:171]
	v_add_f32_e32 v152, 1.0, v152
	v_add_f32_e32 v153, 1.0, v153
	v_add_f32_e32 v148, 1.0, v148
	v_add_f32_e32 v149, 1.0, v149
	v_add_f32_e32 v124, 1.0, v124
	v_add_f32_e32 v125, 1.0, v125
	v_add_f32_e32 v120, 1.0, v120
	v_add_f32_e32 v121, 1.0, v121
	v_rcp_f32_e32 v152, v152
	v_rcp_f32_e32 v153, v153
	v_rcp_f32_e32 v148, v148
	v_rcp_f32_e32 v149, v149
	v_rcp_f32_e32 v124, v124
	v_rcp_f32_e32 v125, v125
	v_rcp_f32_e32 v120, v120
	v_rcp_f32_e32 v121, v121
	s_nop 0
	v_pk_mul_f32 v[12:13], v[12:13], v[152:153]
	v_pk_mul_f32 v[14:15], v[14:15], v[148:149]
	v_pk_mul_f32 v[4:5], v[4:5], v[124:125]
	v_pk_mul_f32 v[6:7], v[6:7], v[120:121]
	v_pk_mul_f32 v[8:9], v[8:9], v[12:13]
	v_pk_mul_f32 v[10:11], v[10:11], v[14:15]
	v_pk_mul_f32 v[0:1], v[0:1], v[4:5]
	v_pk_mul_f32 v[2:3], v[2:3], v[6:7]
	v_cvt_pk_bf16_f32 v8, v8, v9
	v_cvt_pk_bf16_f32 v9, v10, v11
	v_cvt_pk_bf16_f32 v10, v0, v1
	v_cvt_pk_bf16_f32 v11, v2, v3
	global_store_dwordx4 v[82:83], v[8:11], off nt
	s_waitcnt vmcnt(6)
	v_add_f32_e32 v143, v143, v142
	v_add_f32_e32 v145, v144, v145
	v_add_f32_e32 v135, v135, v134
	v_add_f32_e32 v137, v136, v137
	v_add_f32_e32 v131, v131, v130
	v_add_f32_e32 v133, v132, v133
	v_add_f32_e32 v139, v139, v138
	v_add_f32_e32 v141, v140, v141
	v_add_f32_e32 v127, v127, v126
	v_add_f32_e32 v129, v128, v129
	v_add_f32_e32 v109, v109, v108
	v_add_f32_e32 v111, v110, v111
	v_add_f32_e32 v105, v105, v104
	v_add_f32_e32 v107, v106, v107
	v_add_f32_e32 v115, v115, v114
	v_add_f32_e32 v117, v116, v117
	v_add_f32_e32 v142, v143, v145
	v_add_f32_e32 v134, v135, v137
	v_add_f32_e32 v130, v131, v133
	v_add_f32_e32 v138, v139, v141
	v_add_f32_e32 v126, v127, v129
	v_add_f32_e32 v108, v109, v111
	v_add_f32_e32 v104, v105, v107
	v_add_f32_e32 v114, v115, v117
	ds_bpermute_b32 v143, v173, v142
	ds_bpermute_b32 v135, v173, v134
	ds_bpermute_b32 v131, v173, v130
	ds_bpermute_b32 v139, v173, v138
	ds_bpermute_b32 v127, v173, v126
	ds_bpermute_b32 v109, v173, v108
	ds_bpermute_b32 v105, v173, v104
	ds_bpermute_b32 v115, v173, v114
	s_waitcnt lgkmcnt(0)
	v_add_f32_e32 v142, v142, v143
	v_add_f32_e32 v134, v134, v135
	v_add_f32_e32 v130, v130, v131
	v_add_f32_e32 v138, v138, v139
	v_add_f32_e32 v126, v126, v127
	v_add_f32_e32 v108, v108, v109
	v_add_f32_e32 v104, v104, v105
	v_add_f32_e32 v114, v114, v115
	ds_bpermute_b32 v143, v167, v142
	ds_bpermute_b32 v135, v167, v134
	ds_bpermute_b32 v131, v167, v130
	ds_bpermute_b32 v139, v167, v138
	ds_bpermute_b32 v127, v167, v126
	ds_bpermute_b32 v109, v167, v108
	ds_bpermute_b32 v105, v167, v104
	ds_bpermute_b32 v115, v167, v114
	s_waitcnt lgkmcnt(0)
	v_add_f32_e32 v142, v142, v143
	v_add_f32_e32 v134, v134, v135
	v_add_f32_e32 v130, v130, v131
	v_add_f32_e32 v138, v138, v139
	v_add_f32_e32 v126, v126, v127
	v_add_f32_e32 v108, v108, v109
	v_add_f32_e32 v104, v104, v105
	v_add_f32_e32 v114, v114, v115
	v_mov_b32_e32 v78, 0x358637bd
	v_fma_f32 v142, v142, s22, v78
	v_fma_f32 v134, v134, s22, v78
	v_fma_f32 v130, v130, s22, v78
	v_fma_f32 v138, v138, s22, v78
	v_fma_f32 v126, v126, s22, v78
	v_fma_f32 v108, v108, s22, v78
	v_fma_f32 v104, v104, s22, v78
	v_fma_f32 v114, v114, s22, v78
	v_rsq_f32_e32 v142, v142
	v_rsq_f32_e32 v134, v134
	v_rsq_f32_e32 v130, v130
	v_rsq_f32_e32 v138, v138
	v_rsq_f32_e32 v126, v126
	v_rsq_f32_e32 v108, v108
	v_rsq_f32_e32 v104, v104
	v_rsq_f32_e32 v114, v114
	s_nop 0
	ds_write_b32 v79, v142
	ds_write_b32 v79, v134 offset:4
	ds_write_b32 v79, v130 offset:8
	ds_write_b32 v79, v138 offset:12
	ds_write_b32 v79, v126 offset:16
	ds_write_b32 v79, v108 offset:20
	ds_write_b32 v79, v104 offset:24
	ds_write_b32 v79, v114 offset:28
	s_andn2_b64 vcc, exec, s[4:5]
	s_mov_b64 s[6:7], -1
	s_cbranch_vccnz .LBB0_272
	s_waitcnt vmcnt(0)
	s_andn2_b64 vcc, exec, s[8:9]
	s_cbranch_vccnz .LBB0_271
	s_barrier
	s_branch .LBB0_271

.LBB0_1465:
	s_sext_i32_i16 s7, s10
	s_waitcnt lgkmcnt(0)
	s_add_u32 s10, s14, 0x9200000
	s_addc_u32 s11, s15, 0
	s_lshl_b64 s[12:13], s[12:13], 2
	v_bfe_u32 v18, v14, 4, 2
	s_add_u32 s4, s4, s12
	v_and_b32_e32 v15, 15, v14
	v_lshlrev_b32_e32 v16, 4, v18
	v_lshlrev_b32_e32 v14, 2, v14
	s_addc_u32 s5, s5, s13
	v_lshl_or_b32 v203, s18, 6, v15
	v_lshl_or_b32 v15, v15, 6, v16
	s_lshl_b32 s3, s18, 13
	v_and_b32_e32 v14, 32, v14
	v_bitop3_b32 v19, v15, s3, v14 bitop3:0xde
	s_lshl_b32 s3, s17, 5
	s_and_b32 s3, s3, 0x60
	s_add_i32 m0, s40, 0x18000
	v_lshl_add_u64 v[6:7], v[6:7], 0, s[60:61]
	s_lshl_b32 s12, s3, 7
	s_waitcnt vmcnt(2)
	s_barrier
	global_load_lds_dwordx4 v[6:7], off
	v_lshl_add_u64 v[4:5], v[4:5], 0, s[60:61]
	s_add_i32 m0, s40, 0x1a000
	s_add_i32 s44, s40, 0x8000
	s_add_i32 s45, s40, 0xa000
	v_bitop3_b32 v204, v15, s12, v14 bitop3:0xde
	global_load_lds_dwordx4 v[4:5], off
	v_lshl_add_u64 v[0:1], v[0:1], 0, s[60:61]
	s_mov_b32 m0, s44
	s_add_u32 s12, s30, 0x40080
	global_load_lds_dwordx4 v[0:1], off
	v_lshl_add_u64 v[0:1], v[2:3], 0, s[60:61]
	s_mov_b32 m0, s45
	s_addc_u32 s13, s31, 0
	global_load_lds_dwordx4 v[0:1], off
	s_add_i32 m0, s40, 0x1c000
	v_lshl_add_u64 v[0:1], s[12:13], 0, v[112:113]
	global_load_lds_dwordx4 v[0:1], off
	v_lshl_add_u64 v[0:1], s[12:13], 0, v[154:155]
	s_add_i32 m0, s40, 0x1e000
	v_mov_b32_e32 v17, v113
	global_load_lds_dwordx4 v[0:1], off
	v_lshl_add_u64 v[0:1], s[4:5], 0, v[16:17]
	s_mov_b64 s[4:5], 0x1d200000
	v_lshl_add_u64 v[160:161], v[0:1], 0, s[4:5]
	v_lshlrev_b32_e32 v0, 14, v12
	v_and_b32_e32 v0, 0xffff8000, v0
	v_lshl_add_u32 v0, v11, 11, v0
	v_and_b32_e32 v1, 1, v12
	v_lshl_or_b32 v0, v1, 6, v0
	v_lshl_add_u32 v162, v13, 1, v0
	v_lshlrev_b32_e32 v0, 14, v8
	v_and_b32_e32 v0, 0xffff8000, v0
	s_waitcnt vmcnt(6)
	v_lshl_add_u32 v0, v9, 11, v0
	v_and_b32_e32 v1, 1, v8
	s_cmpk_lt_u32 s16, 0x100
	v_lshl_or_b32 v0, v1, 6, v0
	s_cselect_b64 s[12:13], -1, 0
	v_lshl_or_b32 v205, v18, 3, s3
	v_mov_b32_e32 v163, v113
	v_lshl_add_u32 v164, v10, 1, v0
	v_mov_b32_e32 v165, v113
	s_mov_b32 s47, 0
	v_add_u32_e32 v206, 0, v19
	v_lshl_add_u32 v32, s6, 8, v203
	v_mov_b32_e32 v33, 0
	v_lshlrev_b64 v[32:33], 6, v[32:33]
	v_lshl_add_u64 v[32:33], v[160:161], 0, v[32:33]
	global_load_dwordx4 v[0:3], v[32:33], off
	global_load_dwordx4 v[4:7], v[32:33], off offset:1024
	global_load_dwordx4 v[8:11], v[32:33], off offset:2048
	global_load_dwordx4 v[12:15], v[32:33], off offset:3072
	v_lshl_add_u32 v32, s6, 8, v203
	v_add_u32_e32 v32, 0x80, v32
	v_mov_b32_e32 v33, 0
	v_lshlrev_b64 v[32:33], 6, v[32:33]
	v_lshl_add_u64 v[32:33], v[160:161], 0, v[32:33]
	global_load_dwordx4 v[16:19], v[32:33], off
	global_load_dwordx4 v[20:23], v[32:33], off offset:1024
	global_load_dwordx4 v[24:27], v[32:33], off offset:2048
	global_load_dwordx4 v[28:31], v[32:33], off offset:3072
	v_and_b32_e32 v34, 64, v245
	v_add_u32_e32 v36, 64, v34
	v_xor_b32_e32 v34, 16, v245
	v_cmp_lt_i32_e32 vcc, v34, v36
	s_nop 1
	v_cndmask_b32_e32 v34, v245, v34, vcc
	v_lshlrev_b32_e32 v34, 2, v34
	v_xor_b32_e32 v35, 32, v245
	v_cmp_lt_i32_e32 vcc, v35, v36
	s_nop 1
	v_cndmask_b32_e32 v35, v245, v35, vcc
	v_lshlrev_b32_e32 v35, 2, v35
	s_mov_b32 s100, 0x3a800000
	v_lshrrev_b32_e32 v38, 6, v224
	v_and_b32_e32 v39, 15, v224
	v_lshlrev_b32_e32 v38, 9, v38
	v_lshl_or_b32 v38, v39, 5, v38
	v_add_u32_e32 v38, 0x20000, v38
	s_waitcnt vmcnt(0)
	v_add_f32_e32 v1, v1, v0
	v_add_f32_e32 v3, v2, v3
	v_add_f32_e32 v5, v5, v4
	v_add_f32_e32 v7, v6, v7
	v_add_f32_e32 v9, v9, v8
	v_add_f32_e32 v11, v10, v11
	v_add_f32_e32 v13, v13, v12
	v_add_f32_e32 v15, v14, v15
	v_add_f32_e32 v17, v17, v16
	v_add_f32_e32 v19, v18, v19
	v_add_f32_e32 v21, v21, v20
	v_add_f32_e32 v23, v22, v23
	v_add_f32_e32 v25, v25, v24
	v_add_f32_e32 v27, v26, v27
	v_add_f32_e32 v29, v29, v28
	v_add_f32_e32 v31, v30, v31
	v_add_f32_e32 v0, v1, v3
	v_add_f32_e32 v4, v5, v7
	v_add_f32_e32 v8, v9, v11
	v_add_f32_e32 v12, v13, v15
	v_add_f32_e32 v16, v17, v19
	v_add_f32_e32 v20, v21, v23
	v_add_f32_e32 v24, v25, v27
	v_add_f32_e32 v28, v29, v31
	ds_bpermute_b32 v1, v34, v0
	ds_bpermute_b32 v5, v34, v4
	ds_bpermute_b32 v9, v34, v8
	ds_bpermute_b32 v13, v34, v12
	ds_bpermute_b32 v17, v34, v16
	ds_bpermute_b32 v21, v34, v20
	ds_bpermute_b32 v25, v34, v24
	ds_bpermute_b32 v29, v34, v28
	s_waitcnt lgkmcnt(0)
	v_add_f32_e32 v0, v0, v1
	v_add_f32_e32 v4, v4, v5
	v_add_f32_e32 v8, v8, v9
	v_add_f32_e32 v12, v12, v13
	v_add_f32_e32 v16, v16, v17
	v_add_f32_e32 v20, v20, v21
	v_add_f32_e32 v24, v24, v25
	v_add_f32_e32 v28, v28, v29
	ds_bpermute_b32 v1, v35, v0
	ds_bpermute_b32 v5, v35, v4
	ds_bpermute_b32 v9, v35, v8
	ds_bpermute_b32 v13, v35, v12
	ds_bpermute_b32 v17, v35, v16
	ds_bpermute_b32 v21, v35, v20
	ds_bpermute_b32 v25, v35, v24
	ds_bpermute_b32 v29, v35, v28
	s_waitcnt lgkmcnt(0)
	v_add_f32_e32 v0, v0, v1
	v_add_f32_e32 v4, v4, v5
	v_add_f32_e32 v8, v8, v9
	v_add_f32_e32 v12, v12, v13
	v_add_f32_e32 v16, v16, v17
	v_add_f32_e32 v20, v20, v21
	v_add_f32_e32 v24, v24, v25
	v_add_f32_e32 v28, v28, v29
	v_mov_b32_e32 v37, 0x358637bd
	v_fma_f32 v0, v0, s100, v37
	v_fma_f32 v4, v4, s100, v37
	v_fma_f32 v8, v8, s100, v37
	v_fma_f32 v12, v12, s100, v37
	v_fma_f32 v16, v16, s100, v37
	v_fma_f32 v20, v20, s100, v37
	v_fma_f32 v24, v24, s100, v37
	v_fma_f32 v28, v28, s100, v37
	v_rsq_f32_e32 v0, v0
	v_rsq_f32_e32 v4, v4
	v_rsq_f32_e32 v8, v8
	v_rsq_f32_e32 v12, v12
	v_rsq_f32_e32 v16, v16
	v_rsq_f32_e32 v20, v20
	v_rsq_f32_e32 v24, v24
	v_rsq_f32_e32 v28, v28
	s_nop 0
	ds_write_b32 v38, v0
	ds_write_b32 v38, v4 offset:4
	ds_write_b32 v38, v8 offset:8
	ds_write_b32 v38, v12 offset:12
	ds_write_b32 v38, v16 offset:16
	ds_write_b32 v38, v20 offset:20
	ds_write_b32 v38, v24 offset:24
	ds_write_b32 v38, v28 offset:28
	s_waitcnt lgkmcnt(0)
	s_barrier
	s_branch .LBB0_1468

.LBB0_1474:
	v_lshl_add_u32 v176, s6, 8, v203
	v_or_b32_e32 v184, 16, v176
	v_or_b32_e32 v182, 32, v176
	v_or_b32_e32 v180, 48, v176
	v_add_u32_e32 v178, 0x80, v176
	v_add_u32_e32 v174, 0x90, v176
	v_add_u32_e32 v172, 0xa0, v176
	v_lshl_or_b32 v198, s7, 7, v205
	v_add_u32_e32 v166, 0xb0, v176
	v_ashrrev_i32_e32 v199, 31, v198
	v_and_b32_e32 v173, 64, v245
	v_xor_b32_e32 v167, 16, v245
	v_add_u32_e32 v175, 64, v173
	v_cmp_lt_i32_e32 vcc, v167, v175
	s_mov_b32 s22, 0x3a800000
	s_nop 1
	v_cndmask_b32_e32 v167, v245, v167, vcc
	v_lshlrev_b32_e32 v173, 2, v167
	v_xor_b32_e32 v167, 32, v245
	v_cmp_lt_i32_e32 vcc, v167, v175
	v_readlane_b32 s50, v255, 34
	s_nop 1
	v_cndmask_b32_e32 v167, v245, v167, vcc
	v_lshlrev_b32_e32 v167, 2, v167
	v_readlane_b32 s51, v255, 35
	v_lshrrev_b32_e32 v79, 6, v224
	v_and_b32_e32 v78, 15, v224
	v_lshlrev_b32_e32 v79, 9, v79
	v_lshl_or_b32 v79, v78, 5, v79
	v_add_u32_e32 v79, 0x20000, v79
	ds_read_b32 v168, v79
	ds_read_b32 v194, v79 offset:4
	ds_read_b32 v150, v79 offset:8
	ds_read_b32 v146, v79 offset:12
	ds_read_b32 v122, v79 offset:16
	ds_read_b32 v118, v79 offset:20
	ds_read_b32 v80, v79 offset:24
	ds_read_b32 v76, v79 offset:28
	v_lshlrev_b64 v[170:171], 1, v[198:199]
	v_lshl_add_u64 v[170:171], s[10:11], 0, v[170:171]
	s_waitcnt lgkmcnt(0)
	v_pk_mul_f32 v[142:143], v[142:143], v[168:169] op_sel_hi:[1,0]
	v_pk_mul_f32 v[144:145], v[144:145], v[168:169] op_sel_hi:[1,0]
	v_pk_mul_f32 v[134:135], v[134:135], v[168:169] op_sel_hi:[1,0]
	v_pk_mul_f32 v[136:137], v[136:137], v[168:169] op_sel_hi:[1,0]
	v_mul_f32_e32 v152, 0xbfb8aa3b, v142
	v_mul_f32_e32 v153, 0xbfb8aa3b, v143
	v_mul_f32_e32 v148, 0xbfb8aa3b, v144
	v_mul_f32_e32 v149, 0xbfb8aa3b, v145
	v_mul_f32_e32 v124, 0xbfb8aa3b, v134
	v_mul_f32_e32 v125, 0xbfb8aa3b, v135
	v_mul_f32_e32 v120, 0xbfb8aa3b, v136
	v_mul_f32_e32 v121, 0xbfb8aa3b, v137
	v_pk_mul_f32 v[138:139], v[138:139], v[168:169] op_sel_hi:[1,0]
	v_pk_mul_f32 v[140:141], v[140:141], v[168:169] op_sel_hi:[1,0]
	v_pk_mul_f32 v[130:131], v[130:131], v[168:169] op_sel_hi:[1,0]
	v_pk_mul_f32 v[132:133], v[132:133], v[168:169] op_sel_hi:[1,0]
	v_exp_f32_e32 v152, v152
	v_exp_f32_e32 v153, v153
	v_exp_f32_e32 v148, v148
	v_exp_f32_e32 v149, v149
	v_exp_f32_e32 v124, v124
	v_exp_f32_e32 v125, v125
	v_exp_f32_e32 v120, v120
	v_exp_f32_e32 v121, v121
	v_mad_i64_i32 v[82:83], vcc, v176, s52, v[170:171]
	v_add_f32_e32 v152, 1.0, v152
	v_add_f32_e32 v153, 1.0, v153
	v_add_f32_e32 v148, 1.0, v148
	v_add_f32_e32 v149, 1.0, v149
	v_add_f32_e32 v124, 1.0, v124
	v_add_f32_e32 v125, 1.0, v125
	v_add_f32_e32 v120, 1.0, v120
	v_add_f32_e32 v121, 1.0, v121
	v_rcp_f32_e32 v152, v152
	v_rcp_f32_e32 v153, v153
	v_rcp_f32_e32 v148, v148
	v_rcp_f32_e32 v149, v149
	v_rcp_f32_e32 v124, v124
	v_rcp_f32_e32 v125, v125
	v_rcp_f32_e32 v120, v120
	v_rcp_f32_e32 v121, v121
	s_nop 0
	v_pk_mul_f32 v[142:143], v[142:143], v[152:153]
	v_pk_mul_f32 v[144:145], v[144:145], v[148:149]
	v_pk_mul_f32 v[134:135], v[134:135], v[124:125]
	v_pk_mul_f32 v[136:137], v[136:137], v[120:121]
	v_pk_mul_f32 v[138:139], v[138:139], v[142:143]
	v_pk_mul_f32 v[140:141], v[140:141], v[144:145]
	v_pk_mul_f32 v[130:131], v[130:131], v[134:135]
	v_pk_mul_f32 v[132:133], v[132:133], v[136:137]
	v_cvt_pk_bf16_f32 v138, v138, v139
	v_cvt_pk_bf16_f32 v139, v140, v141
	v_cvt_pk_bf16_f32 v140, v130, v131
	v_cvt_pk_bf16_f32 v141, v132, v133
	global_store_dwordx4 v[82:83], v[138:141], off nt
	v_pk_mul_f32 v[126:127], v[126:127], v[194:195] op_sel_hi:[1,0]
	v_pk_mul_f32 v[128:129], v[128:129], v[194:195] op_sel_hi:[1,0]
	v_pk_mul_f32 v[108:109], v[108:109], v[194:195] op_sel_hi:[1,0]
	v_pk_mul_f32 v[110:111], v[110:111], v[194:195] op_sel_hi:[1,0]
	v_mul_f32_e32 v152, 0xbfb8aa3b, v126
	v_mul_f32_e32 v153, 0xbfb8aa3b, v127
	v_mul_f32_e32 v148, 0xbfb8aa3b, v128
	v_mul_f32_e32 v149, 0xbfb8aa3b, v129
	v_mul_f32_e32 v124, 0xbfb8aa3b, v108
	v_mul_f32_e32 v125, 0xbfb8aa3b, v109
	v_mul_f32_e32 v120, 0xbfb8aa3b, v110
	v_mul_f32_e32 v121, 0xbfb8aa3b, v111
	v_pk_mul_f32 v[114:115], v[114:115], v[194:195] op_sel_hi:[1,0]
	v_pk_mul_f32 v[116:117], v[116:117], v[194:195] op_sel_hi:[1,0]
	v_pk_mul_f32 v[104:105], v[104:105], v[194:195] op_sel_hi:[1,0]
	v_pk_mul_f32 v[106:107], v[106:107], v[194:195] op_sel_hi:[1,0]
	v_exp_f32_e32 v152, v152
	v_exp_f32_e32 v153, v153
	v_exp_f32_e32 v148, v148
	v_exp_f32_e32 v149, v149
	v_exp_f32_e32 v124, v124
	v_exp_f32_e32 v125, v125
	v_exp_f32_e32 v120, v120
	v_exp_f32_e32 v121, v121
	v_mad_i64_i32 v[82:83], vcc, v184, s52, v[170:171]
	v_add_f32_e32 v152, 1.0, v152
	v_add_f32_e32 v153, 1.0, v153
	v_add_f32_e32 v148, 1.0, v148
	v_add_f32_e32 v149, 1.0, v149
	v_add_f32_e32 v124, 1.0, v124
	v_add_f32_e32 v125, 1.0, v125
	v_add_f32_e32 v120, 1.0, v120
	v_add_f32_e32 v121, 1.0, v121
	v_rcp_f32_e32 v152, v152
	v_rcp_f32_e32 v153, v153
	v_rcp_f32_e32 v148, v148
	v_rcp_f32_e32 v149, v149
	v_rcp_f32_e32 v124, v124
	v_rcp_f32_e32 v125, v125
	v_rcp_f32_e32 v120, v120
	v_rcp_f32_e32 v121, v121
	s_nop 0
	v_pk_mul_f32 v[126:127], v[126:127], v[152:153]
	v_pk_mul_f32 v[128:129], v[128:129], v[148:149]
	v_pk_mul_f32 v[108:109], v[108:109], v[124:125]
	v_pk_mul_f32 v[110:111], v[110:111], v[120:121]
	v_pk_mul_f32 v[114:115], v[114:115], v[126:127]
	v_pk_mul_f32 v[116:117], v[116:117], v[128:129]
	v_pk_mul_f32 v[104:105], v[104:105], v[108:109]
	v_pk_mul_f32 v[106:107], v[106:107], v[110:111]
	v_cvt_pk_bf16_f32 v114, v114, v115
	v_cvt_pk_bf16_f32 v115, v116, v117
	v_cvt_pk_bf16_f32 v116, v104, v105
	v_cvt_pk_bf16_f32 v117, v106, v107
	global_store_dwordx4 v[82:83], v[114:117], off nt
	v_lshl_add_u32 v196, s16, 8, v203
	v_mov_b32_e32 v197, 0
	v_lshlrev_b64 v[196:197], 6, v[196:197]
	v_lshl_add_u64 v[196:197], v[160:161], 0, v[196:197]
	global_load_dwordx4 v[142:145], v[196:197], off
	global_load_dwordx4 v[134:137], v[196:197], off offset:1024
	global_load_dwordx4 v[130:133], v[196:197], off offset:2048
	global_load_dwordx4 v[138:141], v[196:197], off offset:3072
	v_lshl_add_u32 v196, s16, 8, v203
	v_add_u32_e32 v196, 0x80, v196
	v_mov_b32_e32 v197, 0
	v_lshlrev_b64 v[196:197], 6, v[196:197]
	v_lshl_add_u64 v[196:197], v[160:161], 0, v[196:197]
	global_load_dwordx4 v[126:129], v[196:197], off
	global_load_dwordx4 v[108:111], v[196:197], off offset:1024
	global_load_dwordx4 v[104:107], v[196:197], off offset:2048
	global_load_dwordx4 v[114:117], v[196:197], off offset:3072
	v_pk_mul_f32 v[100:101], v[100:101], v[150:151] op_sel_hi:[1,0]
	v_pk_mul_f32 v[102:103], v[102:103], v[150:151] op_sel_hi:[1,0]
	v_pk_mul_f32 v[92:93], v[92:93], v[150:151] op_sel_hi:[1,0]
	v_pk_mul_f32 v[94:95], v[94:95], v[150:151] op_sel_hi:[1,0]
	v_mul_f32_e32 v152, 0xbfb8aa3b, v100
	v_mul_f32_e32 v153, 0xbfb8aa3b, v101
	v_mul_f32_e32 v148, 0xbfb8aa3b, v102
	v_mul_f32_e32 v149, 0xbfb8aa3b, v103
	v_mul_f32_e32 v124, 0xbfb8aa3b, v92
	v_mul_f32_e32 v125, 0xbfb8aa3b, v93
	v_mul_f32_e32 v120, 0xbfb8aa3b, v94
	v_mul_f32_e32 v121, 0xbfb8aa3b, v95
	v_pk_mul_f32 v[96:97], v[96:97], v[150:151] op_sel_hi:[1,0]
	v_pk_mul_f32 v[98:99], v[98:99], v[150:151] op_sel_hi:[1,0]
	v_pk_mul_f32 v[88:89], v[88:89], v[150:151] op_sel_hi:[1,0]
	v_pk_mul_f32 v[90:91], v[90:91], v[150:151] op_sel_hi:[1,0]
	v_exp_f32_e32 v152, v152
	v_exp_f32_e32 v153, v153
	v_exp_f32_e32 v148, v148
	v_exp_f32_e32 v149, v149
	v_exp_f32_e32 v124, v124
	v_exp_f32_e32 v125, v125
	v_exp_f32_e32 v120, v120
	v_exp_f32_e32 v121, v121
	v_mad_i64_i32 v[82:83], vcc, v182, s52, v[170:171]
	v_add_f32_e32 v152, 1.0, v152
	v_add_f32_e32 v153, 1.0, v153
	v_add_f32_e32 v148, 1.0, v148
	v_add_f32_e32 v149, 1.0, v149
	v_add_f32_e32 v124, 1.0, v124
	v_add_f32_e32 v125, 1.0, v125
	v_add_f32_e32 v120, 1.0, v120
	v_add_f32_e32 v121, 1.0, v121
	v_rcp_f32_e32 v152, v152
	v_rcp_f32_e32 v153, v153
	v_rcp_f32_e32 v148, v148
	v_rcp_f32_e32 v149, v149
	v_rcp_f32_e32 v124, v124
	v_rcp_f32_e32 v125, v125
	v_rcp_f32_e32 v120, v120
	v_rcp_f32_e32 v121, v121
	s_nop 0
	v_pk_mul_f32 v[100:101], v[100:101], v[152:153]
	v_pk_mul_f32 v[102:103], v[102:103], v[148:149]
	v_pk_mul_f32 v[92:93], v[92:93], v[124:125]
	v_pk_mul_f32 v[94:95], v[94:95], v[120:121]
	v_pk_mul_f32 v[96:97], v[96:97], v[100:101]
	v_pk_mul_f32 v[98:99], v[98:99], v[102:103]
	v_pk_mul_f32 v[88:89], v[88:89], v[92:93]
	v_pk_mul_f32 v[90:91], v[90:91], v[94:95]
	v_cvt_pk_bf16_f32 v96, v96, v97
	v_cvt_pk_bf16_f32 v97, v98, v99
	v_cvt_pk_bf16_f32 v98, v88, v89
	v_cvt_pk_bf16_f32 v99, v90, v91
	global_store_dwordx4 v[82:83], v[96:99], off nt
	v_pk_mul_f32 v[84:85], v[84:85], v[146:147] op_sel_hi:[1,0]
	v_pk_mul_f32 v[86:87], v[86:87], v[146:147] op_sel_hi:[1,0]
	v_pk_mul_f32 v[68:69], v[68:69], v[146:147] op_sel_hi:[1,0]
	v_pk_mul_f32 v[70:71], v[70:71], v[146:147] op_sel_hi:[1,0]
	v_mul_f32_e32 v152, 0xbfb8aa3b, v84
	v_mul_f32_e32 v153, 0xbfb8aa3b, v85
	v_mul_f32_e32 v148, 0xbfb8aa3b, v86
	v_mul_f32_e32 v149, 0xbfb8aa3b, v87
	v_mul_f32_e32 v124, 0xbfb8aa3b, v68
	v_mul_f32_e32 v125, 0xbfb8aa3b, v69
	v_mul_f32_e32 v120, 0xbfb8aa3b, v70
	v_mul_f32_e32 v121, 0xbfb8aa3b, v71
	v_pk_mul_f32 v[72:73], v[72:73], v[146:147] op_sel_hi:[1,0]
	v_pk_mul_f32 v[74:75], v[74:75], v[146:147] op_sel_hi:[1,0]
	v_pk_mul_f32 v[64:65], v[64:65], v[146:147] op_sel_hi:[1,0]
	v_pk_mul_f32 v[66:67], v[66:67], v[146:147] op_sel_hi:[1,0]
	v_exp_f32_e32 v152, v152
	v_exp_f32_e32 v153, v153
	v_exp_f32_e32 v148, v148
	v_exp_f32_e32 v149, v149
	v_exp_f32_e32 v124, v124
	v_exp_f32_e32 v125, v125
	v_exp_f32_e32 v120, v120
	v_exp_f32_e32 v121, v121
	v_mad_i64_i32 v[82:83], vcc, v180, s52, v[170:171]
	v_add_f32_e32 v152, 1.0, v152
	v_add_f32_e32 v153, 1.0, v153
	v_add_f32_e32 v148, 1.0, v148
	v_add_f32_e32 v149, 1.0, v149
	v_add_f32_e32 v124, 1.0, v124
	v_add_f32_e32 v125, 1.0, v125
	v_add_f32_e32 v120, 1.0, v120
	v_add_f32_e32 v121, 1.0, v121
	v_rcp_f32_e32 v152, v152
	v_rcp_f32_e32 v153, v153
	v_rcp_f32_e32 v148, v148
	v_rcp_f32_e32 v149, v149
	v_rcp_f32_e32 v124, v124
	v_rcp_f32_e32 v125, v125
	v_rcp_f32_e32 v120, v120
	v_rcp_f32_e32 v121, v121
	s_nop 0
	v_pk_mul_f32 v[84:85], v[84:85], v[152:153]
	v_pk_mul_f32 v[86:87], v[86:87], v[148:149]
	v_pk_mul_f32 v[68:69], v[68:69], v[124:125]
	v_pk_mul_f32 v[70:71], v[70:71], v[120:121]
	v_pk_mul_f32 v[72:73], v[72:73], v[84:85]
	v_pk_mul_f32 v[74:75], v[74:75], v[86:87]
	v_pk_mul_f32 v[64:65], v[64:65], v[68:69]
	v_pk_mul_f32 v[66:67], v[66:67], v[70:71]
	v_cvt_pk_bf16_f32 v72, v72, v73
	v_cvt_pk_bf16_f32 v73, v74, v75
	v_cvt_pk_bf16_f32 v74, v64, v65
	v_cvt_pk_bf16_f32 v75, v66, v67
	global_store_dwordx4 v[82:83], v[72:75], off nt
	v_pk_mul_f32 v[60:61], v[60:61], v[122:123] op_sel_hi:[1,0]
	v_pk_mul_f32 v[62:63], v[62:63], v[122:123] op_sel_hi:[1,0]
	v_pk_mul_f32 v[52:53], v[52:53], v[122:123] op_sel_hi:[1,0]
	v_pk_mul_f32 v[54:55], v[54:55], v[122:123] op_sel_hi:[1,0]
	v_mul_f32_e32 v152, 0xbfb8aa3b, v60
	v_mul_f32_e32 v153, 0xbfb8aa3b, v61
	v_mul_f32_e32 v148, 0xbfb8aa3b, v62
	v_mul_f32_e32 v149, 0xbfb8aa3b, v63
	v_mul_f32_e32 v124, 0xbfb8aa3b, v52
	v_mul_f32_e32 v125, 0xbfb8aa3b, v53
	v_mul_f32_e32 v120, 0xbfb8aa3b, v54
	v_mul_f32_e32 v121, 0xbfb8aa3b, v55
	v_pk_mul_f32 v[56:57], v[56:57], v[122:123] op_sel_hi:[1,0]
	v_pk_mul_f32 v[58:59], v[58:59], v[122:123] op_sel_hi:[1,0]
	v_pk_mul_f32 v[48:49], v[48:49], v[122:123] op_sel_hi:[1,0]
	v_pk_mul_f32 v[50:51], v[50:51], v[122:123] op_sel_hi:[1,0]
	v_exp_f32_e32 v152, v152
	v_exp_f32_e32 v153, v153
	v_exp_f32_e32 v148, v148
	v_exp_f32_e32 v149, v149
	v_exp_f32_e32 v124, v124
	v_exp_f32_e32 v125, v125
	v_exp_f32_e32 v120, v120
	v_exp_f32_e32 v121, v121
	v_mad_i64_i32 v[82:83], vcc, v178, s52, v[170:171]
	v_add_f32_e32 v152, 1.0, v152
	v_add_f32_e32 v153, 1.0, v153
	v_add_f32_e32 v148, 1.0, v148
	v_add_f32_e32 v149, 1.0, v149
	v_add_f32_e32 v124, 1.0, v124
	v_add_f32_e32 v125, 1.0, v125
	v_add_f32_e32 v120, 1.0, v120
	v_add_f32_e32 v121, 1.0, v121
	v_rcp_f32_e32 v152, v152
	v_rcp_f32_e32 v153, v153
	v_rcp_f32_e32 v148, v148
	v_rcp_f32_e32 v149, v149
	v_rcp_f32_e32 v124, v124
	v_rcp_f32_e32 v125, v125
	v_rcp_f32_e32 v120, v120
	v_rcp_f32_e32 v121, v121
	s_nop 0
	v_pk_mul_f32 v[60:61], v[60:61], v[152:153]
	v_pk_mul_f32 v[62:63], v[62:63], v[148:149]
	v_pk_mul_f32 v[52:53], v[52:53], v[124:125]
	v_pk_mul_f32 v[54:55], v[54:55], v[120:121]
	v_pk_mul_f32 v[56:57], v[56:57], v[60:61]
	v_pk_mul_f32 v[58:59], v[58:59], v[62:63]
	v_pk_mul_f32 v[48:49], v[48:49], v[52:53]
	v_pk_mul_f32 v[50:51], v[50:51], v[54:55]
	v_cvt_pk_bf16_f32 v56, v56, v57
	v_cvt_pk_bf16_f32 v57, v58, v59
	v_cvt_pk_bf16_f32 v58, v48, v49
	v_cvt_pk_bf16_f32 v59, v50, v51
	global_store_dwordx4 v[82:83], v[56:59], off nt
	v_pk_mul_f32 v[44:45], v[44:45], v[118:119] op_sel_hi:[1,0]
	v_pk_mul_f32 v[46:47], v[46:47], v[118:119] op_sel_hi:[1,0]
	v_pk_mul_f32 v[36:37], v[36:37], v[118:119] op_sel_hi:[1,0]
	v_pk_mul_f32 v[38:39], v[38:39], v[118:119] op_sel_hi:[1,0]
	v_mul_f32_e32 v152, 0xbfb8aa3b, v44
	v_mul_f32_e32 v153, 0xbfb8aa3b, v45
	v_mul_f32_e32 v148, 0xbfb8aa3b, v46
	v_mul_f32_e32 v149, 0xbfb8aa3b, v47
	v_mul_f32_e32 v124, 0xbfb8aa3b, v36
	v_mul_f32_e32 v125, 0xbfb8aa3b, v37
	v_mul_f32_e32 v120, 0xbfb8aa3b, v38
	v_mul_f32_e32 v121, 0xbfb8aa3b, v39
	v_pk_mul_f32 v[40:41], v[40:41], v[118:119] op_sel_hi:[1,0]
	v_pk_mul_f32 v[42:43], v[42:43], v[118:119] op_sel_hi:[1,0]
	v_pk_mul_f32 v[32:33], v[32:33], v[118:119] op_sel_hi:[1,0]
	v_pk_mul_f32 v[34:35], v[34:35], v[118:119] op_sel_hi:[1,0]
	v_exp_f32_e32 v152, v152
	v_exp_f32_e32 v153, v153
	v_exp_f32_e32 v148, v148
	v_exp_f32_e32 v149, v149
	v_exp_f32_e32 v124, v124
	v_exp_f32_e32 v125, v125
	v_exp_f32_e32 v120, v120
	v_exp_f32_e32 v121, v121
	v_mad_i64_i32 v[82:83], vcc, v174, s52, v[170:171]
	v_add_f32_e32 v152, 1.0, v152
	v_add_f32_e32 v153, 1.0, v153
	v_add_f32_e32 v148, 1.0, v148
	v_add_f32_e32 v149, 1.0, v149
	v_add_f32_e32 v124, 1.0, v124
	v_add_f32_e32 v125, 1.0, v125
	v_add_f32_e32 v120, 1.0, v120
	v_add_f32_e32 v121, 1.0, v121
	v_rcp_f32_e32 v152, v152
	v_rcp_f32_e32 v153, v153
	v_rcp_f32_e32 v148, v148
	v_rcp_f32_e32 v149, v149
	v_rcp_f32_e32 v124, v124
	v_rcp_f32_e32 v125, v125
	v_rcp_f32_e32 v120, v120
	v_rcp_f32_e32 v121, v121
	s_nop 0
	v_pk_mul_f32 v[44:45], v[44:45], v[152:153]
	v_pk_mul_f32 v[46:47], v[46:47], v[148:149]
	v_pk_mul_f32 v[36:37], v[36:37], v[124:125]
	v_pk_mul_f32 v[38:39], v[38:39], v[120:121]
	v_pk_mul_f32 v[40:41], v[40:41], v[44:45]
	v_pk_mul_f32 v[42:43], v[42:43], v[46:47]
	v_pk_mul_f32 v[32:33], v[32:33], v[36:37]
	v_pk_mul_f32 v[34:35], v[34:35], v[38:39]
	v_cvt_pk_bf16_f32 v40, v40, v41
	v_cvt_pk_bf16_f32 v41, v42, v43
	v_cvt_pk_bf16_f32 v42, v32, v33
	v_cvt_pk_bf16_f32 v43, v34, v35
	global_store_dwordx4 v[82:83], v[40:43], off nt
	v_pk_mul_f32 v[28:29], v[28:29], v[80:81] op_sel_hi:[1,0]
	v_pk_mul_f32 v[30:31], v[30:31], v[80:81] op_sel_hi:[1,0]
	v_pk_mul_f32 v[20:21], v[20:21], v[80:81] op_sel_hi:[1,0]
	v_pk_mul_f32 v[22:23], v[22:23], v[80:81] op_sel_hi:[1,0]
	v_mul_f32_e32 v152, 0xbfb8aa3b, v28
	v_mul_f32_e32 v153, 0xbfb8aa3b, v29
	v_mul_f32_e32 v148, 0xbfb8aa3b, v30
	v_mul_f32_e32 v149, 0xbfb8aa3b, v31
	v_mul_f32_e32 v124, 0xbfb8aa3b, v20
	v_mul_f32_e32 v125, 0xbfb8aa3b, v21
	v_mul_f32_e32 v120, 0xbfb8aa3b, v22
	v_mul_f32_e32 v121, 0xbfb8aa3b, v23
	v_pk_mul_f32 v[24:25], v[24:25], v[80:81] op_sel_hi:[1,0]
	v_pk_mul_f32 v[26:27], v[26:27], v[80:81] op_sel_hi:[1,0]
	v_pk_mul_f32 v[16:17], v[16:17], v[80:81] op_sel_hi:[1,0]
	v_pk_mul_f32 v[18:19], v[18:19], v[80:81] op_sel_hi:[1,0]
	v_exp_f32_e32 v152, v152
	v_exp_f32_e32 v153, v153
	v_exp_f32_e32 v148, v148
	v_exp_f32_e32 v149, v149
	v_exp_f32_e32 v124, v124
	v_exp_f32_e32 v125, v125
	v_exp_f32_e32 v120, v120
	v_exp_f32_e32 v121, v121
	v_mad_i64_i32 v[82:83], vcc, v172, s52, v[170:171]
	v_add_f32_e32 v152, 1.0, v152
	v_add_f32_e32 v153, 1.0, v153
	v_add_f32_e32 v148, 1.0, v148
	v_add_f32_e32 v149, 1.0, v149
	v_add_f32_e32 v124, 1.0, v124
	v_add_f32_e32 v125, 1.0, v125
	v_add_f32_e32 v120, 1.0, v120
	v_add_f32_e32 v121, 1.0, v121
	v_rcp_f32_e32 v152, v152
	v_rcp_f32_e32 v153, v153
	v_rcp_f32_e32 v148, v148
	v_rcp_f32_e32 v149, v149
	v_rcp_f32_e32 v124, v124
	v_rcp_f32_e32 v125, v125
	v_rcp_f32_e32 v120, v120
	v_rcp_f32_e32 v121, v121
	s_nop 0
	v_pk_mul_f32 v[28:29], v[28:29], v[152:153]
	v_pk_mul_f32 v[30:31], v[30:31], v[148:149]
	v_pk_mul_f32 v[20:21], v[20:21], v[124:125]
	v_pk_mul_f32 v[22:23], v[22:23], v[120:121]
	v_pk_mul_f32 v[24:25], v[24:25], v[28:29]
	v_pk_mul_f32 v[26:27], v[26:27], v[30:31]
	v_pk_mul_f32 v[16:17], v[16:17], v[20:21]
	v_pk_mul_f32 v[18:19], v[18:19], v[22:23]
	v_cvt_pk_bf16_f32 v24, v24, v25
	v_cvt_pk_bf16_f32 v25, v26, v27
	v_cvt_pk_bf16_f32 v26, v16, v17
	v_cvt_pk_bf16_f32 v27, v18, v19
	global_store_dwordx4 v[82:83], v[24:27], off nt
	v_pk_mul_f32 v[12:13], v[12:13], v[76:77] op_sel_hi:[1,0]
	v_pk_mul_f32 v[14:15], v[14:15], v[76:77] op_sel_hi:[1,0]
	v_pk_mul_f32 v[4:5], v[4:5], v[76:77] op_sel_hi:[1,0]
	v_pk_mul_f32 v[6:7], v[6:7], v[76:77] op_sel_hi:[1,0]
	v_mul_f32_e32 v152, 0xbfb8aa3b, v12
	v_mul_f32_e32 v153, 0xbfb8aa3b, v13
	v_mul_f32_e32 v148, 0xbfb8aa3b, v14
	v_mul_f32_e32 v149, 0xbfb8aa3b, v15
	v_mul_f32_e32 v124, 0xbfb8aa3b, v4
	v_mul_f32_e32 v125, 0xbfb8aa3b, v5
	v_mul_f32_e32 v120, 0xbfb8aa3b, v6
	v_mul_f32_e32 v121, 0xbfb8aa3b, v7
	v_pk_mul_f32 v[8:9], v[8:9], v[76:77] op_sel_hi:[1,0]
	v_pk_mul_f32 v[10:11], v[10:11], v[76:77] op_sel_hi:[1,0]
	v_pk_mul_f32 v[0:1], v[0:1], v[76:77] op_sel_hi:[1,0]
	v_pk_mul_f32 v[2:3], v[2:3], v[76:77] op_sel_hi:[1,0]
	v_exp_f32_e32 v152, v152
	v_exp_f32_e32 v153, v153
	v_exp_f32_e32 v148, v148
	v_exp_f32_e32 v149, v149
	v_exp_f32_e32 v124, v124
	v_exp_f32_e32 v125, v125
	v_exp_f32_e32 v120, v120
	v_exp_f32_e32 v121, v121
	v_mad_i64_i32 v[82:83], vcc, v166, s52, v[170:171]
	v_add_f32_e32 v152, 1.0, v152
	v_add_f32_e32 v153, 1.0, v153
	v_add_f32_e32 v148, 1.0, v148
	v_add_f32_e32 v149, 1.0, v149
	v_add_f32_e32 v124, 1.0, v124
	v_add_f32_e32 v125, 1.0, v125
	v_add_f32_e32 v120, 1.0, v120
	v_add_f32_e32 v121, 1.0, v121
	v_rcp_f32_e32 v152, v152
	v_rcp_f32_e32 v153, v153
	v_rcp_f32_e32 v148, v148
	v_rcp_f32_e32 v149, v149
	v_rcp_f32_e32 v124, v124
	v_rcp_f32_e32 v125, v125
	v_rcp_f32_e32 v120, v120
	v_rcp_f32_e32 v121, v121
	s_nop 0
	v_pk_mul_f32 v[12:13], v[12:13], v[152:153]
	v_pk_mul_f32 v[14:15], v[14:15], v[148:149]
	v_pk_mul_f32 v[4:5], v[4:5], v[124:125]
	v_pk_mul_f32 v[6:7], v[6:7], v[120:121]
	v_pk_mul_f32 v[8:9], v[8:9], v[12:13]
	v_pk_mul_f32 v[10:11], v[10:11], v[14:15]
	v_pk_mul_f32 v[0:1], v[0:1], v[4:5]
	v_pk_mul_f32 v[2:3], v[2:3], v[6:7]
	v_cvt_pk_bf16_f32 v8, v8, v9
	v_cvt_pk_bf16_f32 v9, v10, v11
	v_cvt_pk_bf16_f32 v10, v0, v1
	v_cvt_pk_bf16_f32 v11, v2, v3
	global_store_dwordx4 v[82:83], v[8:11], off nt
	s_waitcnt vmcnt(6)
	v_add_f32_e32 v143, v143, v142
	v_add_f32_e32 v145, v144, v145
	v_add_f32_e32 v135, v135, v134
	v_add_f32_e32 v137, v136, v137
	v_add_f32_e32 v131, v131, v130
	v_add_f32_e32 v133, v132, v133
	v_add_f32_e32 v139, v139, v138
	v_add_f32_e32 v141, v140, v141
	v_add_f32_e32 v127, v127, v126
	v_add_f32_e32 v129, v128, v129
	v_add_f32_e32 v109, v109, v108
	v_add_f32_e32 v111, v110, v111
	v_add_f32_e32 v105, v105, v104
	v_add_f32_e32 v107, v106, v107
	v_add_f32_e32 v115, v115, v114
	v_add_f32_e32 v117, v116, v117
	v_add_f32_e32 v142, v143, v145
	v_add_f32_e32 v134, v135, v137
	v_add_f32_e32 v130, v131, v133
	v_add_f32_e32 v138, v139, v141
	v_add_f32_e32 v126, v127, v129
	v_add_f32_e32 v108, v109, v111
	v_add_f32_e32 v104, v105, v107
	v_add_f32_e32 v114, v115, v117
	ds_bpermute_b32 v143, v173, v142
	ds_bpermute_b32 v135, v173, v134
	ds_bpermute_b32 v131, v173, v130
	ds_bpermute_b32 v139, v173, v138
	ds_bpermute_b32 v127, v173, v126
	ds_bpermute_b32 v109, v173, v108
	ds_bpermute_b32 v105, v173, v104
	ds_bpermute_b32 v115, v173, v114
	s_waitcnt lgkmcnt(0)
	v_add_f32_e32 v142, v142, v143
	v_add_f32_e32 v134, v134, v135
	v_add_f32_e32 v130, v130, v131
	v_add_f32_e32 v138, v138, v139
	v_add_f32_e32 v126, v126, v127
	v_add_f32_e32 v108, v108, v109
	v_add_f32_e32 v104, v104, v105
	v_add_f32_e32 v114, v114, v115
	ds_bpermute_b32 v143, v167, v142
	ds_bpermute_b32 v135, v167, v134
	ds_bpermute_b32 v131, v167, v130
	ds_bpermute_b32 v139, v167, v138
	ds_bpermute_b32 v127, v167, v126
	ds_bpermute_b32 v109, v167, v108
	ds_bpermute_b32 v105, v167, v104
	ds_bpermute_b32 v115, v167, v114
	s_waitcnt lgkmcnt(0)
	v_add_f32_e32 v142, v142, v143
	v_add_f32_e32 v134, v134, v135
	v_add_f32_e32 v130, v130, v131
	v_add_f32_e32 v138, v138, v139
	v_add_f32_e32 v126, v126, v127
	v_add_f32_e32 v108, v108, v109
	v_add_f32_e32 v104, v104, v105
	v_add_f32_e32 v114, v114, v115
	v_mov_b32_e32 v78, 0x358637bd
	v_fma_f32 v142, v142, s22, v78
	v_fma_f32 v134, v134, s22, v78
	v_fma_f32 v130, v130, s22, v78
	v_fma_f32 v138, v138, s22, v78
	v_fma_f32 v126, v126, s22, v78
	v_fma_f32 v108, v108, s22, v78
	v_fma_f32 v104, v104, s22, v78
	v_fma_f32 v114, v114, s22, v78
	v_rsq_f32_e32 v142, v142
	v_rsq_f32_e32 v134, v134
	v_rsq_f32_e32 v130, v130
	v_rsq_f32_e32 v138, v138
	v_rsq_f32_e32 v126, v126
	v_rsq_f32_e32 v108, v108
	v_rsq_f32_e32 v104, v104
	v_rsq_f32_e32 v114, v114
	s_nop 0
	ds_write_b32 v79, v142
	ds_write_b32 v79, v134 offset:4
	ds_write_b32 v79, v130 offset:8
	ds_write_b32 v79, v138 offset:12
	ds_write_b32 v79, v126 offset:16
	ds_write_b32 v79, v108 offset:20
	ds_write_b32 v79, v104 offset:24
	ds_write_b32 v79, v114 offset:28
	s_andn2_b64 vcc, exec, s[4:5]
	s_mov_b64 s[6:7], -1
	s_cbranch_vccnz .LBB0_1467
	s_waitcnt vmcnt(0)
	s_andn2_b64 vcc, exec, s[8:9]
	s_cbranch_vccnz .LBB0_1466
	s_barrier
	s_branch .LBB0_1466
